# layer-0 norm: context rows share one shift/scale set (all loads up front); fold-GEMM workgroups leave their norm rows to the other 384
# speedup vs baseline: 1.0121x; 1.0121x over previous
.LBB0_35:
	s_mov_b64 s[22:23], exec
	v_readlane_b32 s0, v248, 41
	v_lshrrev_b32_e32 v210, 6, v0
	v_readlane_b32 s1, v246, 41
	v_readlane_b32 s36, v248, 50
	v_readfirstlane_b32 s2, v210
	v_readlane_b32 s37, v248, 51
	v_and_b32_e32 v211, 63, v0
	v_lshlrev_b32_e32 v212, 3, v211
	v_lshlrev_b32_e32 v211, 4, v211
	s_add_i32 s34, s0, s2
	s_lshl_b32 s35, s1, 2
	s_cmp_eq_u32 s35, 0x800
	s_cbranch_scc0 .Lnorm0_gen
	s_cmp_lt_u32 s34, 0x200
	s_cbranch_scc1 .Lnorm0_done
	global_load_dwordx4 v[82:85], v211, s[36:37]
	global_load_dwordx4 v[86:89], v211, s[36:37] offset:1024
	global_load_dwordx4 v[90:93], v211, s[36:37] offset:2048
	global_load_dwordx4 v[94:97], v211, s[36:37] offset:3072
	s_mov_b32 s46, 0
	s_mul_i32 s46, s46, 0x3000
	s_add_u32 s50, s4, s46
	s_addc_u32 s51, s5, 0
	s_add_u32 s54, s50, 0x1000
	s_addc_u32 s55, s51, 0
	global_load_dwordx4 v[98:101], v211, s[50:51]
	global_load_dwordx4 v[102:105], v211, s[50:51] offset:1024
	global_load_dwordx4 v[106:109], v211, s[50:51] offset:2048
	global_load_dwordx4 v[110:113], v211, s[50:51] offset:3072
	global_load_dwordx4 v[114:117], v211, s[54:55]
	global_load_dwordx4 v[118:121], v211, s[54:55] offset:1024
	global_load_dwordx4 v[122:125], v211, s[54:55] offset:2048
	global_load_dwordx4 v[126:129], v211, s[54:55] offset:3072
	s_lshr_b32 s46, s34, 10
	s_add_i32 s46, s46, 1
	s_mul_i32 s46, s46, 0x3000
	s_add_u32 s50, s4, s46
	s_addc_u32 s51, s5, 0
	s_add_u32 s54, s50, 0x1000
	s_addc_u32 s55, s51, 0
	global_load_dwordx4 v[178:181], v211, s[50:51]
	global_load_dwordx4 v[182:185], v211, s[50:51] offset:1024
	global_load_dwordx4 v[186:189], v211, s[50:51] offset:2048
	global_load_dwordx4 v[190:193], v211, s[50:51] offset:3072
	global_load_dwordx4 v[194:197], v211, s[54:55]
	global_load_dwordx4 v[198:201], v211, s[54:55] offset:1024
	global_load_dwordx4 v[202:205], v211, s[54:55] offset:2048
	global_load_dwordx4 v[206:209], v211, s[54:55] offset:3072
	s_add_i32 s40, s34, 0x0
	s_lshl_b32 s46, s40, 12
	s_add_u32 s48, s76, s46
	s_addc_u32 s49, s77, 0
	global_load_dwordx4 v[2:5], v211, s[48:49]
	global_load_dwordx4 v[6:9], v211, s[48:49] offset:1024
	global_load_dwordx4 v[10:13], v211, s[48:49] offset:2048
	global_load_dwordx4 v[14:17], v211, s[48:49] offset:3072
	s_add_i32 s41, s34, 0x800
	s_lshl_b32 s46, s41, 12
	s_add_u32 s48, s76, s46
	s_addc_u32 s49, s77, 0
	global_load_dwordx4 v[18:21], v211, s[48:49]
	global_load_dwordx4 v[22:25], v211, s[48:49] offset:1024
	global_load_dwordx4 v[26:29], v211, s[48:49] offset:2048
	global_load_dwordx4 v[30:33], v211, s[48:49] offset:3072
	s_add_i32 s42, s34, 0x1000
	s_lshl_b32 s46, s42, 12
	s_add_u32 s48, s76, s46
	s_addc_u32 s49, s77, 0
	global_load_dwordx4 v[34:37], v211, s[48:49]
	global_load_dwordx4 v[38:41], v211, s[48:49] offset:1024
	global_load_dwordx4 v[42:45], v211, s[48:49] offset:2048
	global_load_dwordx4 v[46:49], v211, s[48:49] offset:3072
	s_add_i32 s43, s34, 0x1800
	s_lshl_b32 s46, s43, 12
	s_add_u32 s48, s76, s46
	s_addc_u32 s49, s77, 0
	global_load_dwordx4 v[50:53], v211, s[48:49]
	global_load_dwordx4 v[54:57], v211, s[48:49] offset:1024
	global_load_dwordx4 v[58:61], v211, s[48:49] offset:2048
	global_load_dwordx4 v[62:65], v211, s[48:49] offset:3072
	s_add_i32 s44, s34, 0x2000
	s_lshl_b32 s46, s34, 12
	s_add_u32 s48, s78, s46
	s_addc_u32 s49, s79, 0
	global_load_dwordx4 v[66:69], v211, s[48:49]
	global_load_dwordx4 v[70:73], v211, s[48:49] offset:1024
	global_load_dwordx4 v[74:77], v211, s[48:49] offset:2048
	global_load_dwordx4 v[78:81], v211, s[48:49] offset:3072
	s_waitcnt vmcnt(16)
	v_mul_f32_e32 v213, v2, v2
	v_fmac_f32_e32 v213, v3, v3
	v_fmac_f32_e32 v213, v4, v4
	v_fmac_f32_e32 v213, v5, v5
	v_fmac_f32_e32 v213, v6, v6
	v_fmac_f32_e32 v213, v7, v7
	v_fmac_f32_e32 v213, v8, v8
	v_fmac_f32_e32 v213, v9, v9
	v_fmac_f32_e32 v213, v10, v10
	v_fmac_f32_e32 v213, v11, v11
	v_fmac_f32_e32 v213, v12, v12
	v_fmac_f32_e32 v213, v13, v13
	v_fmac_f32_e32 v213, v14, v14
	v_fmac_f32_e32 v213, v15, v15
	v_fmac_f32_e32 v213, v16, v16
	v_fmac_f32_e32 v213, v17, v17
	s_nop 1
	v_add_f32_dpp v213, v213, v213 quad_perm:[1,0,3,2] row_mask:0xf bank_mask:0xf
	s_nop 1
	v_add_f32_dpp v213, v213, v213 quad_perm:[2,3,0,1] row_mask:0xf bank_mask:0xf
	s_nop 1
	v_add_f32_dpp v213, v213, v213 row_ror:4 row_mask:0xf bank_mask:0xf
	s_nop 1
	v_add_f32_dpp v213, v213, v213 row_ror:8 row_mask:0xf bank_mask:0xf
	s_nop 1
	v_add_f32_dpp v213, v213, v213 row_bcast:15 row_mask:0xa bank_mask:0xf
	s_nop 1
	v_add_f32_dpp v213, v213, v213 row_bcast:31 row_mask:0xc bank_mask:0xf
	s_nop 1
	v_readlane_b32 s47, v213, 63
	s_mul_i32 s56, s40, 0x880
	s_add_u32 s56, s8, s56
	s_addc_u32 s57, s9, 0
	v_mov_b32_e32 v214, s47
	v_fmamk_f32 v214, v214, 0x3a800000, v148
	v_rsq_f32_e32 v214, v214
	s_nop 0
	v_pk_mul_f32 v[2:3], v[2:3], v[214:215] op_sel_hi:[1,0]
	v_pk_add_f32 v[114:115], v[114:115], 1.0 op_sel_hi:[1,0]
	v_pk_mul_f32 v[2:3], v[2:3], v[82:83]
	v_pk_fma_f32 v[2:3], v[2:3], v[114:115], v[98:99]
	v_pk_mul_f32 v[4:5], v[4:5], v[214:215] op_sel_hi:[1,0]
	v_pk_add_f32 v[116:117], v[116:117], 1.0 op_sel_hi:[1,0]
	v_pk_mul_f32 v[4:5], v[4:5], v[84:85]
	v_pk_fma_f32 v[4:5], v[4:5], v[116:117], v[100:101]
	v_pk_mul_f32 v[6:7], v[6:7], v[214:215] op_sel_hi:[1,0]
	v_pk_add_f32 v[118:119], v[118:119], 1.0 op_sel_hi:[1,0]
	v_pk_mul_f32 v[6:7], v[6:7], v[86:87]
	v_pk_fma_f32 v[6:7], v[6:7], v[118:119], v[102:103]
	v_pk_mul_f32 v[8:9], v[8:9], v[214:215] op_sel_hi:[1,0]
	v_pk_add_f32 v[120:121], v[120:121], 1.0 op_sel_hi:[1,0]
	v_pk_mul_f32 v[8:9], v[8:9], v[88:89]
	v_pk_fma_f32 v[8:9], v[8:9], v[120:121], v[104:105]
	v_pk_mul_f32 v[10:11], v[10:11], v[214:215] op_sel_hi:[1,0]
	v_pk_add_f32 v[122:123], v[122:123], 1.0 op_sel_hi:[1,0]
	v_pk_mul_f32 v[10:11], v[10:11], v[90:91]
	v_pk_fma_f32 v[10:11], v[10:11], v[122:123], v[106:107]
	v_pk_mul_f32 v[12:13], v[12:13], v[214:215] op_sel_hi:[1,0]
	v_pk_add_f32 v[124:125], v[124:125], 1.0 op_sel_hi:[1,0]
	v_pk_mul_f32 v[12:13], v[12:13], v[92:93]
	v_pk_fma_f32 v[12:13], v[12:13], v[124:125], v[108:109]
	v_pk_mul_f32 v[14:15], v[14:15], v[214:215] op_sel_hi:[1,0]
	v_pk_add_f32 v[126:127], v[126:127], 1.0 op_sel_hi:[1,0]
	v_pk_mul_f32 v[14:15], v[14:15], v[94:95]
	v_pk_fma_f32 v[14:15], v[14:15], v[126:127], v[110:111]
	v_pk_mul_f32 v[16:17], v[16:17], v[214:215] op_sel_hi:[1,0]
	v_pk_add_f32 v[128:129], v[128:129], 1.0 op_sel_hi:[1,0]
	v_pk_mul_f32 v[16:17], v[16:17], v[96:97]
	v_pk_fma_f32 v[16:17], v[16:17], v[128:129], v[112:113]
	v_cvt_pk_bf16_f32 v216, v2, v3
	v_cvt_pk_bf16_f32 v217, v4, v5
	v_cvt_pk_bf16_f32 v218, v6, v7
	v_cvt_pk_bf16_f32 v219, v8, v9
	v_cvt_pk_bf16_f32 v220, v10, v11
	v_cvt_pk_bf16_f32 v221, v12, v13
	v_cvt_pk_bf16_f32 v222, v14, v15
	v_cvt_pk_bf16_f32 v223, v16, v17
	global_store_dwordx2 v212, v[216:217], s[56:57]
	global_store_dwordx2 v212, v[218:219], s[56:57] offset:512
	global_store_dwordx2 v212, v[220:221], s[56:57] offset:1024
	global_store_dwordx2 v212, v[222:223], s[56:57] offset:1536
	s_waitcnt vmcnt(16)
	v_mul_f32_e32 v213, v18, v18
	v_fmac_f32_e32 v213, v19, v19
	v_fmac_f32_e32 v213, v20, v20
	v_fmac_f32_e32 v213, v21, v21
	v_fmac_f32_e32 v213, v22, v22
	v_fmac_f32_e32 v213, v23, v23
	v_fmac_f32_e32 v213, v24, v24
	v_fmac_f32_e32 v213, v25, v25
	v_fmac_f32_e32 v213, v26, v26
	v_fmac_f32_e32 v213, v27, v27
	v_fmac_f32_e32 v213, v28, v28
	v_fmac_f32_e32 v213, v29, v29
	v_fmac_f32_e32 v213, v30, v30
	v_fmac_f32_e32 v213, v31, v31
	v_fmac_f32_e32 v213, v32, v32
	v_fmac_f32_e32 v213, v33, v33
	s_nop 1
	v_add_f32_dpp v213, v213, v213 quad_perm:[1,0,3,2] row_mask:0xf bank_mask:0xf
	s_nop 1
	v_add_f32_dpp v213, v213, v213 quad_perm:[2,3,0,1] row_mask:0xf bank_mask:0xf
	s_nop 1
	v_add_f32_dpp v213, v213, v213 row_ror:4 row_mask:0xf bank_mask:0xf
	s_nop 1
	v_add_f32_dpp v213, v213, v213 row_ror:8 row_mask:0xf bank_mask:0xf
	s_nop 1
	v_add_f32_dpp v213, v213, v213 row_bcast:15 row_mask:0xa bank_mask:0xf
	s_nop 1
	v_add_f32_dpp v213, v213, v213 row_bcast:31 row_mask:0xc bank_mask:0xf
	s_nop 1
	v_readlane_b32 s47, v213, 63
	s_mul_i32 s56, s41, 0x880
	s_add_u32 s56, s8, s56
	s_addc_u32 s57, s9, 0
	v_mov_b32_e32 v214, s47
	v_fmamk_f32 v214, v214, 0x3a800000, v148
	v_rsq_f32_e32 v214, v214
	s_nop 0
	v_pk_mul_f32 v[18:19], v[18:19], v[214:215] op_sel_hi:[1,0]
	v_pk_mul_f32 v[18:19], v[18:19], v[82:83]
	v_pk_fma_f32 v[18:19], v[18:19], v[114:115], v[98:99]
	v_pk_mul_f32 v[20:21], v[20:21], v[214:215] op_sel_hi:[1,0]
	v_pk_mul_f32 v[20:21], v[20:21], v[84:85]
	v_pk_fma_f32 v[20:21], v[20:21], v[116:117], v[100:101]
	v_pk_mul_f32 v[22:23], v[22:23], v[214:215] op_sel_hi:[1,0]
	v_pk_mul_f32 v[22:23], v[22:23], v[86:87]
	v_pk_fma_f32 v[22:23], v[22:23], v[118:119], v[102:103]
	v_pk_mul_f32 v[24:25], v[24:25], v[214:215] op_sel_hi:[1,0]
	v_pk_mul_f32 v[24:25], v[24:25], v[88:89]
	v_pk_fma_f32 v[24:25], v[24:25], v[120:121], v[104:105]
	v_pk_mul_f32 v[26:27], v[26:27], v[214:215] op_sel_hi:[1,0]
	v_pk_mul_f32 v[26:27], v[26:27], v[90:91]
	v_pk_fma_f32 v[26:27], v[26:27], v[122:123], v[106:107]
	v_pk_mul_f32 v[28:29], v[28:29], v[214:215] op_sel_hi:[1,0]
	v_pk_mul_f32 v[28:29], v[28:29], v[92:93]
	v_pk_fma_f32 v[28:29], v[28:29], v[124:125], v[108:109]
	v_pk_mul_f32 v[30:31], v[30:31], v[214:215] op_sel_hi:[1,0]
	v_pk_mul_f32 v[30:31], v[30:31], v[94:95]
	v_pk_fma_f32 v[30:31], v[30:31], v[126:127], v[110:111]
	v_pk_mul_f32 v[32:33], v[32:33], v[214:215] op_sel_hi:[1,0]
	v_pk_mul_f32 v[32:33], v[32:33], v[96:97]
	v_pk_fma_f32 v[32:33], v[32:33], v[128:129], v[112:113]
	v_cvt_pk_bf16_f32 v216, v18, v19
	v_cvt_pk_bf16_f32 v217, v20, v21
	v_cvt_pk_bf16_f32 v218, v22, v23
	v_cvt_pk_bf16_f32 v219, v24, v25
	v_cvt_pk_bf16_f32 v220, v26, v27
	v_cvt_pk_bf16_f32 v221, v28, v29
	v_cvt_pk_bf16_f32 v222, v30, v31
	v_cvt_pk_bf16_f32 v223, v32, v33
	global_store_dwordx2 v212, v[216:217], s[56:57]
	global_store_dwordx2 v212, v[218:219], s[56:57] offset:512
	global_store_dwordx2 v212, v[220:221], s[56:57] offset:1024
	global_store_dwordx2 v212, v[222:223], s[56:57] offset:1536
	s_waitcnt vmcnt(16)
	v_mul_f32_e32 v213, v34, v34
	v_fmac_f32_e32 v213, v35, v35
	v_fmac_f32_e32 v213, v36, v36
	v_fmac_f32_e32 v213, v37, v37
	v_fmac_f32_e32 v213, v38, v38
	v_fmac_f32_e32 v213, v39, v39
	v_fmac_f32_e32 v213, v40, v40
	v_fmac_f32_e32 v213, v41, v41
	v_fmac_f32_e32 v213, v42, v42
	v_fmac_f32_e32 v213, v43, v43
	v_fmac_f32_e32 v213, v44, v44
	v_fmac_f32_e32 v213, v45, v45
	v_fmac_f32_e32 v213, v46, v46
	v_fmac_f32_e32 v213, v47, v47
	v_fmac_f32_e32 v213, v48, v48
	v_fmac_f32_e32 v213, v49, v49
	s_nop 1
	v_add_f32_dpp v213, v213, v213 quad_perm:[1,0,3,2] row_mask:0xf bank_mask:0xf
	s_nop 1
	v_add_f32_dpp v213, v213, v213 quad_perm:[2,3,0,1] row_mask:0xf bank_mask:0xf
	s_nop 1
	v_add_f32_dpp v213, v213, v213 row_ror:4 row_mask:0xf bank_mask:0xf
	s_nop 1
	v_add_f32_dpp v213, v213, v213 row_ror:8 row_mask:0xf bank_mask:0xf
	s_nop 1
	v_add_f32_dpp v213, v213, v213 row_bcast:15 row_mask:0xa bank_mask:0xf
	s_nop 1
	v_add_f32_dpp v213, v213, v213 row_bcast:31 row_mask:0xc bank_mask:0xf
	s_nop 1
	v_readlane_b32 s47, v213, 63
	s_mul_i32 s56, s42, 0x880
	s_add_u32 s56, s8, s56
	s_addc_u32 s57, s9, 0
	v_mov_b32_e32 v214, s47
	v_fmamk_f32 v214, v214, 0x3a800000, v148
	v_rsq_f32_e32 v214, v214
	s_nop 0
	v_pk_mul_f32 v[34:35], v[34:35], v[214:215] op_sel_hi:[1,0]
	v_pk_mul_f32 v[34:35], v[34:35], v[82:83]
	v_pk_fma_f32 v[34:35], v[34:35], v[114:115], v[98:99]
	v_pk_mul_f32 v[36:37], v[36:37], v[214:215] op_sel_hi:[1,0]
	v_pk_mul_f32 v[36:37], v[36:37], v[84:85]
	v_pk_fma_f32 v[36:37], v[36:37], v[116:117], v[100:101]
	v_pk_mul_f32 v[38:39], v[38:39], v[214:215] op_sel_hi:[1,0]
	v_pk_mul_f32 v[38:39], v[38:39], v[86:87]
	v_pk_fma_f32 v[38:39], v[38:39], v[118:119], v[102:103]
	v_pk_mul_f32 v[40:41], v[40:41], v[214:215] op_sel_hi:[1,0]
	v_pk_mul_f32 v[40:41], v[40:41], v[88:89]
	v_pk_fma_f32 v[40:41], v[40:41], v[120:121], v[104:105]
	v_pk_mul_f32 v[42:43], v[42:43], v[214:215] op_sel_hi:[1,0]
	v_pk_mul_f32 v[42:43], v[42:43], v[90:91]
	v_pk_fma_f32 v[42:43], v[42:43], v[122:123], v[106:107]
	v_pk_mul_f32 v[44:45], v[44:45], v[214:215] op_sel_hi:[1,0]
	v_pk_mul_f32 v[44:45], v[44:45], v[92:93]
	v_pk_fma_f32 v[44:45], v[44:45], v[124:125], v[108:109]
	v_pk_mul_f32 v[46:47], v[46:47], v[214:215] op_sel_hi:[1,0]
	v_pk_mul_f32 v[46:47], v[46:47], v[94:95]
	v_pk_fma_f32 v[46:47], v[46:47], v[126:127], v[110:111]
	v_pk_mul_f32 v[48:49], v[48:49], v[214:215] op_sel_hi:[1,0]
	v_pk_mul_f32 v[48:49], v[48:49], v[96:97]
	v_pk_fma_f32 v[48:49], v[48:49], v[128:129], v[112:113]
	v_cvt_pk_bf16_f32 v216, v34, v35
	v_cvt_pk_bf16_f32 v217, v36, v37
	v_cvt_pk_bf16_f32 v218, v38, v39
	v_cvt_pk_bf16_f32 v219, v40, v41
	v_cvt_pk_bf16_f32 v220, v42, v43
	v_cvt_pk_bf16_f32 v221, v44, v45
	v_cvt_pk_bf16_f32 v222, v46, v47
	v_cvt_pk_bf16_f32 v223, v48, v49
	global_store_dwordx2 v212, v[216:217], s[56:57]
	global_store_dwordx2 v212, v[218:219], s[56:57] offset:512
	global_store_dwordx2 v212, v[220:221], s[56:57] offset:1024
	global_store_dwordx2 v212, v[222:223], s[56:57] offset:1536
	s_waitcnt vmcnt(16)
	v_mul_f32_e32 v213, v50, v50
	v_fmac_f32_e32 v213, v51, v51
	v_fmac_f32_e32 v213, v52, v52
	v_fmac_f32_e32 v213, v53, v53
	v_fmac_f32_e32 v213, v54, v54
	v_fmac_f32_e32 v213, v55, v55
	v_fmac_f32_e32 v213, v56, v56
	v_fmac_f32_e32 v213, v57, v57
	v_fmac_f32_e32 v213, v58, v58
	v_fmac_f32_e32 v213, v59, v59
	v_fmac_f32_e32 v213, v60, v60
	v_fmac_f32_e32 v213, v61, v61
	v_fmac_f32_e32 v213, v62, v62
	v_fmac_f32_e32 v213, v63, v63
	v_fmac_f32_e32 v213, v64, v64
	v_fmac_f32_e32 v213, v65, v65
	s_nop 1
	v_add_f32_dpp v213, v213, v213 quad_perm:[1,0,3,2] row_mask:0xf bank_mask:0xf
	s_nop 1
	v_add_f32_dpp v213, v213, v213 quad_perm:[2,3,0,1] row_mask:0xf bank_mask:0xf
	s_nop 1
	v_add_f32_dpp v213, v213, v213 row_ror:4 row_mask:0xf bank_mask:0xf
	s_nop 1
	v_add_f32_dpp v213, v213, v213 row_ror:8 row_mask:0xf bank_mask:0xf
	s_nop 1
	v_add_f32_dpp v213, v213, v213 row_bcast:15 row_mask:0xa bank_mask:0xf
	s_nop 1
	v_add_f32_dpp v213, v213, v213 row_bcast:31 row_mask:0xc bank_mask:0xf
	s_nop 1
	v_readlane_b32 s47, v213, 63
	s_mul_i32 s56, s43, 0x880
	s_add_u32 s56, s8, s56
	s_addc_u32 s57, s9, 0
	v_mov_b32_e32 v214, s47
	v_fmamk_f32 v214, v214, 0x3a800000, v148
	v_rsq_f32_e32 v214, v214
	s_nop 0
	v_pk_mul_f32 v[50:51], v[50:51], v[214:215] op_sel_hi:[1,0]
	v_pk_mul_f32 v[50:51], v[50:51], v[82:83]
	v_pk_fma_f32 v[50:51], v[50:51], v[114:115], v[98:99]
	v_pk_mul_f32 v[52:53], v[52:53], v[214:215] op_sel_hi:[1,0]
	v_pk_mul_f32 v[52:53], v[52:53], v[84:85]
	v_pk_fma_f32 v[52:53], v[52:53], v[116:117], v[100:101]
	v_pk_mul_f32 v[54:55], v[54:55], v[214:215] op_sel_hi:[1,0]
	v_pk_mul_f32 v[54:55], v[54:55], v[86:87]
	v_pk_fma_f32 v[54:55], v[54:55], v[118:119], v[102:103]
	v_pk_mul_f32 v[56:57], v[56:57], v[214:215] op_sel_hi:[1,0]
	v_pk_mul_f32 v[56:57], v[56:57], v[88:89]
	v_pk_fma_f32 v[56:57], v[56:57], v[120:121], v[104:105]
	v_pk_mul_f32 v[58:59], v[58:59], v[214:215] op_sel_hi:[1,0]
	v_pk_mul_f32 v[58:59], v[58:59], v[90:91]
	v_pk_fma_f32 v[58:59], v[58:59], v[122:123], v[106:107]
	v_pk_mul_f32 v[60:61], v[60:61], v[214:215] op_sel_hi:[1,0]
	v_pk_mul_f32 v[60:61], v[60:61], v[92:93]
	v_pk_fma_f32 v[60:61], v[60:61], v[124:125], v[108:109]
	v_pk_mul_f32 v[62:63], v[62:63], v[214:215] op_sel_hi:[1,0]
	v_pk_mul_f32 v[62:63], v[62:63], v[94:95]
	v_pk_fma_f32 v[62:63], v[62:63], v[126:127], v[110:111]
	v_pk_mul_f32 v[64:65], v[64:65], v[214:215] op_sel_hi:[1,0]
	v_pk_mul_f32 v[64:65], v[64:65], v[96:97]
	v_pk_fma_f32 v[64:65], v[64:65], v[128:129], v[112:113]
	v_cvt_pk_bf16_f32 v216, v50, v51
	v_cvt_pk_bf16_f32 v217, v52, v53
	v_cvt_pk_bf16_f32 v218, v54, v55
	v_cvt_pk_bf16_f32 v219, v56, v57
	v_cvt_pk_bf16_f32 v220, v58, v59
	v_cvt_pk_bf16_f32 v221, v60, v61
	v_cvt_pk_bf16_f32 v222, v62, v63
	v_cvt_pk_bf16_f32 v223, v64, v65
	global_store_dwordx2 v212, v[216:217], s[56:57]
	global_store_dwordx2 v212, v[218:219], s[56:57] offset:512
	global_store_dwordx2 v212, v[220:221], s[56:57] offset:1024
	global_store_dwordx2 v212, v[222:223], s[56:57] offset:1536
	s_waitcnt vmcnt(16)
	v_mul_f32_e32 v213, v66, v66
	v_fmac_f32_e32 v213, v67, v67
	v_fmac_f32_e32 v213, v68, v68
	v_fmac_f32_e32 v213, v69, v69
	v_fmac_f32_e32 v213, v70, v70
	v_fmac_f32_e32 v213, v71, v71
	v_fmac_f32_e32 v213, v72, v72
	v_fmac_f32_e32 v213, v73, v73
	v_fmac_f32_e32 v213, v74, v74
	v_fmac_f32_e32 v213, v75, v75
	v_fmac_f32_e32 v213, v76, v76
	v_fmac_f32_e32 v213, v77, v77
	v_fmac_f32_e32 v213, v78, v78
	v_fmac_f32_e32 v213, v79, v79
	v_fmac_f32_e32 v213, v80, v80
	v_fmac_f32_e32 v213, v81, v81
	s_nop 1
	v_add_f32_dpp v213, v213, v213 quad_perm:[1,0,3,2] row_mask:0xf bank_mask:0xf
	s_nop 1
	v_add_f32_dpp v213, v213, v213 quad_perm:[2,3,0,1] row_mask:0xf bank_mask:0xf
	s_nop 1
	v_add_f32_dpp v213, v213, v213 row_ror:4 row_mask:0xf bank_mask:0xf
	s_nop 1
	v_add_f32_dpp v213, v213, v213 row_ror:8 row_mask:0xf bank_mask:0xf
	s_nop 1
	v_add_f32_dpp v213, v213, v213 row_bcast:15 row_mask:0xa bank_mask:0xf
	s_nop 1
	v_add_f32_dpp v213, v213, v213 row_bcast:31 row_mask:0xc bank_mask:0xf
	s_nop 1
	v_readlane_b32 s47, v213, 63
	s_mul_i32 s56, s44, 0x880
	s_add_u32 s56, s8, s56
	s_addc_u32 s57, s9, 0
	v_mov_b32_e32 v214, s47
	v_fmamk_f32 v214, v214, 0x3a800000, v148
	v_rsq_f32_e32 v214, v214
	s_nop 0
	v_pk_mul_f32 v[66:67], v[66:67], v[214:215] op_sel_hi:[1,0]
	v_pk_add_f32 v[194:195], v[194:195], 1.0 op_sel_hi:[1,0]
	v_pk_mul_f32 v[66:67], v[66:67], v[82:83]
	v_pk_fma_f32 v[66:67], v[66:67], v[194:195], v[178:179]
	v_pk_mul_f32 v[68:69], v[68:69], v[214:215] op_sel_hi:[1,0]
	v_pk_add_f32 v[196:197], v[196:197], 1.0 op_sel_hi:[1,0]
	v_pk_mul_f32 v[68:69], v[68:69], v[84:85]
	v_pk_fma_f32 v[68:69], v[68:69], v[196:197], v[180:181]
	v_pk_mul_f32 v[70:71], v[70:71], v[214:215] op_sel_hi:[1,0]
	v_pk_add_f32 v[198:199], v[198:199], 1.0 op_sel_hi:[1,0]
	v_pk_mul_f32 v[70:71], v[70:71], v[86:87]
	v_pk_fma_f32 v[70:71], v[70:71], v[198:199], v[182:183]
	v_pk_mul_f32 v[72:73], v[72:73], v[214:215] op_sel_hi:[1,0]
	v_pk_add_f32 v[200:201], v[200:201], 1.0 op_sel_hi:[1,0]
	v_pk_mul_f32 v[72:73], v[72:73], v[88:89]
	v_pk_fma_f32 v[72:73], v[72:73], v[200:201], v[184:185]
	v_pk_mul_f32 v[74:75], v[74:75], v[214:215] op_sel_hi:[1,0]
	v_pk_add_f32 v[202:203], v[202:203], 1.0 op_sel_hi:[1,0]
	v_pk_mul_f32 v[74:75], v[74:75], v[90:91]
	v_pk_fma_f32 v[74:75], v[74:75], v[202:203], v[186:187]
	v_pk_mul_f32 v[76:77], v[76:77], v[214:215] op_sel_hi:[1,0]
	v_pk_add_f32 v[204:205], v[204:205], 1.0 op_sel_hi:[1,0]
	v_pk_mul_f32 v[76:77], v[76:77], v[92:93]
	v_pk_fma_f32 v[76:77], v[76:77], v[204:205], v[188:189]
	v_pk_mul_f32 v[78:79], v[78:79], v[214:215] op_sel_hi:[1,0]
	v_pk_add_f32 v[206:207], v[206:207], 1.0 op_sel_hi:[1,0]
	v_pk_mul_f32 v[78:79], v[78:79], v[94:95]
	v_pk_fma_f32 v[78:79], v[78:79], v[206:207], v[190:191]
	v_pk_mul_f32 v[80:81], v[80:81], v[214:215] op_sel_hi:[1,0]
	v_pk_add_f32 v[208:209], v[208:209], 1.0 op_sel_hi:[1,0]
	v_pk_mul_f32 v[80:81], v[80:81], v[96:97]
	v_pk_fma_f32 v[80:81], v[80:81], v[208:209], v[192:193]
	v_cvt_pk_bf16_f32 v216, v66, v67
	v_cvt_pk_bf16_f32 v217, v68, v69
	v_cvt_pk_bf16_f32 v218, v70, v71
	v_cvt_pk_bf16_f32 v219, v72, v73
	v_cvt_pk_bf16_f32 v220, v74, v75
	v_cvt_pk_bf16_f32 v221, v76, v77
	v_cvt_pk_bf16_f32 v222, v78, v79
	v_cvt_pk_bf16_f32 v223, v80, v81
	global_store_dwordx2 v212, v[216:217], s[56:57]
	global_store_dwordx2 v212, v[218:219], s[56:57] offset:512
	global_store_dwordx2 v212, v[220:221], s[56:57] offset:1024
	global_store_dwordx2 v212, v[222:223], s[56:57] offset:1536
	s_sub_u32 s34, s34, 0x200
	s_lshr_b32 s46, s34, 9
	s_lshl_b32 s46, s46, 11
	s_and_b32 s47, s34, 0x1ff
	s_add_i32 s40, s46, s47
	s_add_i32 s41, s34, 0x600
	s_lshr_b32 s46, s41, 9
	s_lshl_b32 s46, s46, 11
	s_and_b32 s47, s41, 0x1ff
	s_add_i32 s46, s46, s47
	s_cmp_lt_u32 s41, 0xa00
	s_cselect_b32 s41, s46, s40
	s_sub_u32 s46, s40, 0x2000
	s_lshr_b32 s46, s46, 10
	s_add_i32 s46, s46, 1
	s_cmp_lt_u32 s40, 0x2000
	s_cselect_b32 s46, 0, s46
	s_mul_i32 s46, s46, 0x3000
	s_add_u32 s50, s4, s46
	s_addc_u32 s51, s5, 0
	s_add_u32 s54, s50, 0x1000
	s_addc_u32 s55, s51, 0
	global_load_dwordx4 v[98:101], v211, s[50:51]
	global_load_dwordx4 v[102:105], v211, s[50:51] offset:1024
	global_load_dwordx4 v[106:109], v211, s[50:51] offset:2048
	global_load_dwordx4 v[110:113], v211, s[50:51] offset:3072
	global_load_dwordx4 v[114:117], v211, s[54:55]
	global_load_dwordx4 v[118:121], v211, s[54:55] offset:1024
	global_load_dwordx4 v[122:125], v211, s[54:55] offset:2048
	global_load_dwordx4 v[126:129], v211, s[54:55] offset:3072
	s_sub_u32 s46, s41, 0x2000
	s_lshr_b32 s46, s46, 10
	s_add_i32 s46, s46, 1
	s_cmp_lt_u32 s41, 0x2000
	s_cselect_b32 s46, 0, s46
	s_mul_i32 s46, s46, 0x3000
	s_add_u32 s50, s4, s46
	s_addc_u32 s51, s5, 0
	s_add_u32 s54, s50, 0x1000
	s_addc_u32 s55, s51, 0
	global_load_dwordx4 v[178:181], v211, s[50:51]
	global_load_dwordx4 v[182:185], v211, s[50:51] offset:1024
	global_load_dwordx4 v[186:189], v211, s[50:51] offset:2048
	global_load_dwordx4 v[190:193], v211, s[50:51] offset:3072
	global_load_dwordx4 v[194:197], v211, s[54:55]
	global_load_dwordx4 v[198:201], v211, s[54:55] offset:1024
	global_load_dwordx4 v[202:205], v211, s[54:55] offset:2048
	global_load_dwordx4 v[206:209], v211, s[54:55] offset:3072
	s_cmp_lt_u32 s40, 0x2000
	s_cselect_b32 s48, s76, s78
	s_cselect_b32 s49, s77, s79
	s_cselect_b32 s46, 0, 0x2000
	s_sub_u32 s46, s40, s46
	s_lshl_b32 s46, s46, 12
	s_add_u32 s48, s48, s46
	s_addc_u32 s49, s49, 0
	global_load_dwordx4 v[2:5], v211, s[48:49]
	global_load_dwordx4 v[6:9], v211, s[48:49] offset:1024
	global_load_dwordx4 v[10:13], v211, s[48:49] offset:2048
	global_load_dwordx4 v[14:17], v211, s[48:49] offset:3072
	s_cmp_lt_u32 s41, 0x2000
	s_cselect_b32 s48, s76, s78
	s_cselect_b32 s49, s77, s79
	s_cselect_b32 s46, 0, 0x2000
	s_sub_u32 s46, s41, s46
	s_lshl_b32 s46, s46, 12
	s_add_u32 s48, s48, s46
	s_addc_u32 s49, s49, 0
	global_load_dwordx4 v[18:21], v211, s[48:49]
	global_load_dwordx4 v[22:25], v211, s[48:49] offset:1024
	global_load_dwordx4 v[26:29], v211, s[48:49] offset:2048
	global_load_dwordx4 v[30:33], v211, s[48:49] offset:3072
	s_waitcnt vmcnt(4)
	v_mul_f32_e32 v213, v2, v2
	v_fmac_f32_e32 v213, v3, v3
	v_fmac_f32_e32 v213, v4, v4
	v_fmac_f32_e32 v213, v5, v5
	v_fmac_f32_e32 v213, v6, v6
	v_fmac_f32_e32 v213, v7, v7
	v_fmac_f32_e32 v213, v8, v8
	v_fmac_f32_e32 v213, v9, v9
	v_fmac_f32_e32 v213, v10, v10
	v_fmac_f32_e32 v213, v11, v11
	v_fmac_f32_e32 v213, v12, v12
	v_fmac_f32_e32 v213, v13, v13
	v_fmac_f32_e32 v213, v14, v14
	v_fmac_f32_e32 v213, v15, v15
	v_fmac_f32_e32 v213, v16, v16
	v_fmac_f32_e32 v213, v17, v17
	s_nop 1
	v_add_f32_dpp v213, v213, v213 quad_perm:[1,0,3,2] row_mask:0xf bank_mask:0xf
	s_nop 1
	v_add_f32_dpp v213, v213, v213 quad_perm:[2,3,0,1] row_mask:0xf bank_mask:0xf
	s_nop 1
	v_add_f32_dpp v213, v213, v213 row_ror:4 row_mask:0xf bank_mask:0xf
	s_nop 1
	v_add_f32_dpp v213, v213, v213 row_ror:8 row_mask:0xf bank_mask:0xf
	s_nop 1
	v_add_f32_dpp v213, v213, v213 row_bcast:15 row_mask:0xa bank_mask:0xf
	s_nop 1
	v_add_f32_dpp v213, v213, v213 row_bcast:31 row_mask:0xc bank_mask:0xf
	s_nop 1
	v_readlane_b32 s47, v213, 63
	s_mul_i32 s56, s40, 0x880
	s_add_u32 s56, s8, s56
	s_addc_u32 s57, s9, 0
	v_mov_b32_e32 v214, s47
	v_fmamk_f32 v214, v214, 0x3a800000, v148
	v_rsq_f32_e32 v214, v214
	s_nop 0
	v_pk_mul_f32 v[2:3], v[2:3], v[214:215] op_sel_hi:[1,0]
	v_pk_add_f32 v[114:115], v[114:115], 1.0 op_sel_hi:[1,0]
	v_pk_mul_f32 v[2:3], v[2:3], v[82:83]
	v_pk_fma_f32 v[2:3], v[2:3], v[114:115], v[98:99]
	v_pk_mul_f32 v[4:5], v[4:5], v[214:215] op_sel_hi:[1,0]
	v_pk_add_f32 v[116:117], v[116:117], 1.0 op_sel_hi:[1,0]
	v_pk_mul_f32 v[4:5], v[4:5], v[84:85]
	v_pk_fma_f32 v[4:5], v[4:5], v[116:117], v[100:101]
	v_pk_mul_f32 v[6:7], v[6:7], v[214:215] op_sel_hi:[1,0]
	v_pk_add_f32 v[118:119], v[118:119], 1.0 op_sel_hi:[1,0]
	v_pk_mul_f32 v[6:7], v[6:7], v[86:87]
	v_pk_fma_f32 v[6:7], v[6:7], v[118:119], v[102:103]
	v_pk_mul_f32 v[8:9], v[8:9], v[214:215] op_sel_hi:[1,0]
	v_pk_add_f32 v[120:121], v[120:121], 1.0 op_sel_hi:[1,0]
	v_pk_mul_f32 v[8:9], v[8:9], v[88:89]
	v_pk_fma_f32 v[8:9], v[8:9], v[120:121], v[104:105]
	v_pk_mul_f32 v[10:11], v[10:11], v[214:215] op_sel_hi:[1,0]
	v_pk_add_f32 v[122:123], v[122:123], 1.0 op_sel_hi:[1,0]
	v_pk_mul_f32 v[10:11], v[10:11], v[90:91]
	v_pk_fma_f32 v[10:11], v[10:11], v[122:123], v[106:107]
	v_pk_mul_f32 v[12:13], v[12:13], v[214:215] op_sel_hi:[1,0]
	v_pk_add_f32 v[124:125], v[124:125], 1.0 op_sel_hi:[1,0]
	v_pk_mul_f32 v[12:13], v[12:13], v[92:93]
	v_pk_fma_f32 v[12:13], v[12:13], v[124:125], v[108:109]
	v_pk_mul_f32 v[14:15], v[14:15], v[214:215] op_sel_hi:[1,0]
	v_pk_add_f32 v[126:127], v[126:127], 1.0 op_sel_hi:[1,0]
	v_pk_mul_f32 v[14:15], v[14:15], v[94:95]
	v_pk_fma_f32 v[14:15], v[14:15], v[126:127], v[110:111]
	v_pk_mul_f32 v[16:17], v[16:17], v[214:215] op_sel_hi:[1,0]
	v_pk_add_f32 v[128:129], v[128:129], 1.0 op_sel_hi:[1,0]
	v_pk_mul_f32 v[16:17], v[16:17], v[96:97]
	v_pk_fma_f32 v[16:17], v[16:17], v[128:129], v[112:113]
	v_cvt_pk_bf16_f32 v216, v2, v3
	v_cvt_pk_bf16_f32 v217, v4, v5
	v_cvt_pk_bf16_f32 v218, v6, v7
	v_cvt_pk_bf16_f32 v219, v8, v9
	v_cvt_pk_bf16_f32 v220, v10, v11
	v_cvt_pk_bf16_f32 v221, v12, v13
	v_cvt_pk_bf16_f32 v222, v14, v15
	v_cvt_pk_bf16_f32 v223, v16, v17
	global_store_dwordx2 v212, v[216:217], s[56:57]
	global_store_dwordx2 v212, v[218:219], s[56:57] offset:512
	global_store_dwordx2 v212, v[220:221], s[56:57] offset:1024
	global_store_dwordx2 v212, v[222:223], s[56:57] offset:1536
	s_waitcnt vmcnt(4)
	v_mul_f32_e32 v213, v18, v18
	v_fmac_f32_e32 v213, v19, v19
	v_fmac_f32_e32 v213, v20, v20
	v_fmac_f32_e32 v213, v21, v21
	v_fmac_f32_e32 v213, v22, v22
	v_fmac_f32_e32 v213, v23, v23
	v_fmac_f32_e32 v213, v24, v24
	v_fmac_f32_e32 v213, v25, v25
	v_fmac_f32_e32 v213, v26, v26
	v_fmac_f32_e32 v213, v27, v27
	v_fmac_f32_e32 v213, v28, v28
	v_fmac_f32_e32 v213, v29, v29
	v_fmac_f32_e32 v213, v30, v30
	v_fmac_f32_e32 v213, v31, v31
	v_fmac_f32_e32 v213, v32, v32
	v_fmac_f32_e32 v213, v33, v33
	s_nop 1
	v_add_f32_dpp v213, v213, v213 quad_perm:[1,0,3,2] row_mask:0xf bank_mask:0xf
	s_nop 1
	v_add_f32_dpp v213, v213, v213 quad_perm:[2,3,0,1] row_mask:0xf bank_mask:0xf
	s_nop 1
	v_add_f32_dpp v213, v213, v213 row_ror:4 row_mask:0xf bank_mask:0xf
	s_nop 1
	v_add_f32_dpp v213, v213, v213 row_ror:8 row_mask:0xf bank_mask:0xf
	s_nop 1
	v_add_f32_dpp v213, v213, v213 row_bcast:15 row_mask:0xa bank_mask:0xf
	s_nop 1
	v_add_f32_dpp v213, v213, v213 row_bcast:31 row_mask:0xc bank_mask:0xf
	s_nop 1
	v_readlane_b32 s47, v213, 63
	s_mul_i32 s56, s41, 0x880
	s_add_u32 s56, s8, s56
	s_addc_u32 s57, s9, 0
	v_mov_b32_e32 v214, s47
	v_fmamk_f32 v214, v214, 0x3a800000, v148
	v_rsq_f32_e32 v214, v214
	s_nop 0
	v_pk_mul_f32 v[18:19], v[18:19], v[214:215] op_sel_hi:[1,0]
	v_pk_add_f32 v[194:195], v[194:195], 1.0 op_sel_hi:[1,0]
	v_pk_mul_f32 v[18:19], v[18:19], v[82:83]
	v_pk_fma_f32 v[18:19], v[18:19], v[194:195], v[178:179]
	v_pk_mul_f32 v[20:21], v[20:21], v[214:215] op_sel_hi:[1,0]
	v_pk_add_f32 v[196:197], v[196:197], 1.0 op_sel_hi:[1,0]
	v_pk_mul_f32 v[20:21], v[20:21], v[84:85]
	v_pk_fma_f32 v[20:21], v[20:21], v[196:197], v[180:181]
	v_pk_mul_f32 v[22:23], v[22:23], v[214:215] op_sel_hi:[1,0]
	v_pk_add_f32 v[198:199], v[198:199], 1.0 op_sel_hi:[1,0]
	v_pk_mul_f32 v[22:23], v[22:23], v[86:87]
	v_pk_fma_f32 v[22:23], v[22:23], v[198:199], v[182:183]
	v_pk_mul_f32 v[24:25], v[24:25], v[214:215] op_sel_hi:[1,0]
	v_pk_add_f32 v[200:201], v[200:201], 1.0 op_sel_hi:[1,0]
	v_pk_mul_f32 v[24:25], v[24:25], v[88:89]
	v_pk_fma_f32 v[24:25], v[24:25], v[200:201], v[184:185]
	v_pk_mul_f32 v[26:27], v[26:27], v[214:215] op_sel_hi:[1,0]
	v_pk_add_f32 v[202:203], v[202:203], 1.0 op_sel_hi:[1,0]
	v_pk_mul_f32 v[26:27], v[26:27], v[90:91]
	v_pk_fma_f32 v[26:27], v[26:27], v[202:203], v[186:187]
	v_pk_mul_f32 v[28:29], v[28:29], v[214:215] op_sel_hi:[1,0]
	v_pk_add_f32 v[204:205], v[204:205], 1.0 op_sel_hi:[1,0]
	v_pk_mul_f32 v[28:29], v[28:29], v[92:93]
	v_pk_fma_f32 v[28:29], v[28:29], v[204:205], v[188:189]
	v_pk_mul_f32 v[30:31], v[30:31], v[214:215] op_sel_hi:[1,0]
	v_pk_add_f32 v[206:207], v[206:207], 1.0 op_sel_hi:[1,0]
	v_pk_mul_f32 v[30:31], v[30:31], v[94:95]
	v_pk_fma_f32 v[30:31], v[30:31], v[206:207], v[190:191]
	v_pk_mul_f32 v[32:33], v[32:33], v[214:215] op_sel_hi:[1,0]
	v_pk_add_f32 v[208:209], v[208:209], 1.0 op_sel_hi:[1,0]
	v_pk_mul_f32 v[32:33], v[32:33], v[96:97]
	v_pk_fma_f32 v[32:33], v[32:33], v[208:209], v[192:193]
	v_cvt_pk_bf16_f32 v216, v18, v19
	v_cvt_pk_bf16_f32 v217, v20, v21
	v_cvt_pk_bf16_f32 v218, v22, v23
	v_cvt_pk_bf16_f32 v219, v24, v25
	v_cvt_pk_bf16_f32 v220, v26, v27
	v_cvt_pk_bf16_f32 v221, v28, v29
	v_cvt_pk_bf16_f32 v222, v30, v31
	v_cvt_pk_bf16_f32 v223, v32, v33
	global_store_dwordx2 v212, v[216:217], s[56:57]
	global_store_dwordx2 v212, v[218:219], s[56:57] offset:512
	global_store_dwordx2 v212, v[220:221], s[56:57] offset:1024
	global_store_dwordx2 v212, v[222:223], s[56:57] offset:1536
	s_branch .Lnorm0_done
.Lnorm0_gen:
	global_load_dwordx4 v[82:85], v211, s[36:37]
	global_load_dwordx4 v[86:89], v211, s[36:37] offset:1024
	global_load_dwordx4 v[90:93], v211, s[36:37] offset:2048
	global_load_dwordx4 v[94:97], v211, s[36:37] offset:3072
